# lnv: the 16 global_load_ushort of each iteration issued together up front (out-of-line block), originals become copies, vmcnt recomputed; placement preserved
# speedup vs baseline: 1.0076x; 1.0076x over previous
.Llnv_pfd:
	v_add_co_u32_e32 v52, vcc, 0xea80000, v66
	v_lshl_add_u64 v[50:51], v[36:37], 0, s[8:9]
	s_nop 0
	v_addc_co_u32_e32 v53, vcc, 0, v67, vcc
	v_add_co_u32_e32 v56, vcc, 0xea81000, v66
	s_waitcnt vmcnt(7)
	v_mov_b64_e32 v[52:53], v[100:101]
	v_mov_b64_e32 v[54:55], v[102:103]
	v_addc_co_u32_e32 v57, vcc, 0, v67, vcc
	s_waitcnt vmcnt(6)
	v_mov_b64_e32 v[56:57], v[104:105]
	v_mov_b64_e32 v[58:59], v[106:107]
	v_lshl_add_u64 v[48:49], v[38:39], 0, s[8:9]
	s_add_u32 s8, s8, 0x8000
	s_addc_u32 s9, s9, 0
	s_cmp_eq_u32 s8, 0x20000
	v_and_b32_e32 v62, 0xffff0000, v52
	v_and_b32_e32 v68, 0xffff0000, v54
	v_lshlrev_b32_e32 v60, 16, v52
	v_lshlrev_b32_e32 v61, 16, v56
	v_and_b32_e32 v63, 0xffff0000, v56
	v_lshlrev_b32_e32 v64, 16, v53
	v_and_b32_e32 v56, 0xffff0000, v53
	v_lshlrev_b32_e32 v53, 16, v58
	v_lshlrev_b32_e32 v52, 16, v54
	v_and_b32_e32 v69, 0xffff0000, v58
	v_and_b32_e32 v58, 0xffff0000, v55
	v_mov_b32_e32 v72, v62
	v_mov_b32_e32 v73, v68
	v_lshlrev_b32_e32 v70, 16, v55
	v_mov_b32_e32 v54, v60
	v_mov_b32_e32 v55, v52
	v_pk_mul_f32 v[72:73], v[72:73], v[72:73]
	v_mov_b32_e32 v74, v56
	v_mov_b32_e32 v75, v58
	v_pk_fma_f32 v[54:55], v[54:55], v[54:55], v[72:73]
	v_mov_b32_e32 v72, v64
	v_mov_b32_e32 v73, v70
	v_pk_mul_f32 v[74:75], v[74:75], v[74:75]
	v_lshlrev_b32_e32 v65, 16, v57
	v_pk_fma_f32 v[72:73], v[72:73], v[72:73], v[74:75]
	v_and_b32_e32 v57, 0xffff0000, v57
	v_pk_add_f32 v[54:55], v[54:55], v[72:73]
	v_lshlrev_b32_e32 v71, 16, v59
	v_and_b32_e32 v59, 0xffff0000, v59
	v_add_f32_e32 v11, v54, v55
	v_pk_add_f32 v[54:55], v[60:61], v[62:63]
	v_pk_add_f32 v[72:73], v[64:65], v[56:57]
	v_pk_add_f32 v[74:75], v[70:71], v[58:59]
	v_pk_add_f32 v[54:55], v[54:55], v[72:73]
	v_pk_add_f32 v[72:73], v[52:53], v[68:69]
	v_mov_b32_e32 v68, v63
	v_mov_b32_e32 v58, v57
	v_mov_b32_e32 v52, v61
	v_pk_mul_f32 v[60:61], v[68:69], v[68:69]
	v_mov_b32_e32 v70, v65
	v_pk_mul_f32 v[56:57], v[58:59], v[58:59]
	v_pk_add_f32 v[72:73], v[72:73], v[74:75]
	v_pk_fma_f32 v[52:53], v[52:53], v[52:53], v[60:61]
	v_pk_fma_f32 v[56:57], v[70:71], v[70:71], v[56:57]
	v_pk_add_f32 v[54:55], v[54:55], v[72:73]
	v_pk_add_f32 v[52:53], v[52:53], v[56:57]
	ds_bpermute_b32 v15, v245, v11
	v_add_f32_e32 v13, v52, v53
	ds_bpermute_b32 v52, v245, v54
	ds_bpermute_b32 v53, v245, v55
	s_waitcnt lgkmcnt(0)
	v_add_f32_e32 v11, v11, v15
	ds_bpermute_b32 v15, v245, v13
	v_pk_add_f32 v[52:53], v[54:55], v[52:53]
	v_add_co_u32_e32 v54, vcc, s80, v66
	s_waitcnt lgkmcnt(0)
	v_add_f32_e32 v13, v13, v15
	v_addc_co_u32_e32 v55, vcc, 0, v67, vcc
	v_add_co_u32_e32 v58, vcc, s81, v66
	s_waitcnt vmcnt(5)
	v_mov_b64_e32 v[54:55], v[108:109]
	v_mov_b64_e32 v[56:57], v[110:111]
	v_addc_co_u32_e32 v59, vcc, 0, v67, vcc
	s_waitcnt vmcnt(4)
	v_mov_b64_e32 v[58:59], v[112:113]
	v_mov_b64_e32 v[60:61], v[114:115]
	v_and_b32_e32 v64, 0xffff0000, v54
	v_and_b32_e32 v70, 0xffff0000, v56
	v_lshlrev_b32_e32 v62, 16, v54
	v_lshlrev_b32_e32 v63, 16, v58
	v_and_b32_e32 v65, 0xffff0000, v58
	v_lshlrev_b32_e32 v68, 16, v55
	v_and_b32_e32 v58, 0xffff0000, v55
	v_lshlrev_b32_e32 v55, 16, v60
	v_lshlrev_b32_e32 v54, 16, v56
	v_and_b32_e32 v71, 0xffff0000, v60
	v_and_b32_e32 v60, 0xffff0000, v57
	v_mov_b32_e32 v74, v64
	v_mov_b32_e32 v75, v70
	v_lshlrev_b32_e32 v72, 16, v57
	v_mov_b32_e32 v56, v62
	v_mov_b32_e32 v57, v54
	v_pk_mul_f32 v[74:75], v[74:75], v[74:75]
	v_mov_b32_e32 v76, v58
	v_mov_b32_e32 v77, v60
	v_pk_fma_f32 v[56:57], v[56:57], v[56:57], v[74:75]
	v_mov_b32_e32 v74, v68
	v_mov_b32_e32 v75, v72
	v_pk_mul_f32 v[76:77], v[76:77], v[76:77]
	v_lshlrev_b32_e32 v69, 16, v59
	v_pk_fma_f32 v[74:75], v[74:75], v[74:75], v[76:77]
	v_and_b32_e32 v59, 0xffff0000, v59
	v_pk_add_f32 v[56:57], v[56:57], v[74:75]
	v_lshlrev_b32_e32 v73, 16, v61
	v_and_b32_e32 v61, 0xffff0000, v61
	v_add_f32_e32 v15, v56, v57
	v_pk_add_f32 v[56:57], v[62:63], v[64:65]
	v_pk_add_f32 v[74:75], v[68:69], v[58:59]
	v_pk_add_f32 v[76:77], v[72:73], v[60:61]
	v_pk_add_f32 v[56:57], v[56:57], v[74:75]
	v_pk_add_f32 v[74:75], v[54:55], v[70:71]
	v_mov_b32_e32 v70, v65
	v_mov_b32_e32 v60, v59
	v_mov_b32_e32 v54, v63
	v_pk_mul_f32 v[62:63], v[70:71], v[70:71]
	v_mov_b32_e32 v72, v69
	v_pk_mul_f32 v[58:59], v[60:61], v[60:61]
	v_pk_add_f32 v[74:75], v[74:75], v[76:77]
	v_pk_fma_f32 v[54:55], v[54:55], v[54:55], v[62:63]
	v_pk_fma_f32 v[58:59], v[72:73], v[72:73], v[58:59]
	v_pk_add_f32 v[56:57], v[56:57], v[74:75]
	v_pk_add_f32 v[54:55], v[54:55], v[58:59]
	ds_bpermute_b32 v21, v245, v15
	v_add_f32_e32 v19, v54, v55
	ds_bpermute_b32 v54, v245, v56
	ds_bpermute_b32 v55, v245, v57
	s_waitcnt lgkmcnt(2)
	v_add_f32_e32 v15, v15, v21
	ds_bpermute_b32 v21, v245, v19
	s_waitcnt lgkmcnt(1)
	v_pk_add_f32 v[56:57], v[56:57], v[54:55]
	v_add_co_u32_e32 v54, vcc, s82, v66
	s_waitcnt lgkmcnt(0)
	v_add_f32_e32 v19, v19, v21
	v_addc_co_u32_e32 v55, vcc, 0, v67, vcc
	s_waitcnt vmcnt(3)
	v_mov_b64_e32 v[58:59], v[116:117]
	v_mov_b64_e32 v[60:61], v[118:119]
	v_add_co_u32_e32 v54, vcc, s83, v66
	v_and_b32_e32 v68, 0xffff0000, v58
	v_addc_co_u32_e32 v55, vcc, 0, v67, vcc
	s_waitcnt vmcnt(2)
	v_mov_b64_e32 v[62:63], v[120:121]
	v_mov_b64_e32 v[64:65], v[122:123]
	v_and_b32_e32 v72, 0xffff0000, v60
	v_lshlrev_b32_e32 v54, 16, v58
	v_lshlrev_b32_e32 v70, 16, v59
	v_lshlrev_b32_e32 v58, 16, v60
	v_mov_b32_e32 v76, v68
	v_mov_b32_e32 v77, v72
	v_lshlrev_b32_e32 v74, 16, v61
	v_mov_b32_e32 v60, v54
	v_pk_mul_f32 v[76:77], v[76:77], v[76:77]
	v_lshlrev_b32_e32 v55, 16, v62
	v_and_b32_e32 v69, 0xffff0000, v62
	v_and_b32_e32 v62, 0xffff0000, v59
	v_lshlrev_b32_e32 v59, 16, v64
	v_and_b32_e32 v73, 0xffff0000, v64
	v_and_b32_e32 v64, 0xffff0000, v61
	v_mov_b32_e32 v61, v58
	v_mov_b32_e32 v78, v62
	v_mov_b32_e32 v79, v64
	v_pk_fma_f32 v[60:61], v[60:61], v[60:61], v[76:77]
	v_mov_b32_e32 v76, v70
	v_mov_b32_e32 v77, v74
	v_pk_mul_f32 v[78:79], v[78:79], v[78:79]
	v_lshlrev_b32_e32 v71, 16, v63
	v_pk_fma_f32 v[76:77], v[76:77], v[76:77], v[78:79]
	v_and_b32_e32 v63, 0xffff0000, v63
	v_pk_add_f32 v[60:61], v[60:61], v[76:77]
	v_pk_add_f32 v[76:77], v[70:71], v[62:63]
	v_add_f32_e32 v21, v60, v61
	v_pk_add_f32 v[60:61], v[54:55], v[68:69]
	v_lshlrev_b32_e32 v75, 16, v65
	v_and_b32_e32 v65, 0xffff0000, v65
	v_pk_add_f32 v[60:61], v[60:61], v[76:77]
	v_pk_add_f32 v[76:77], v[58:59], v[72:73]
	v_mov_b32_e32 v72, v69
	v_pk_add_f32 v[78:79], v[74:75], v[64:65]
	v_mov_b32_e32 v58, v55
	v_pk_mul_f32 v[54:55], v[72:73], v[72:73]
	v_mov_b32_e32 v64, v63
	v_pk_fma_f32 v[54:55], v[58:59], v[58:59], v[54:55]
	v_mov_b32_e32 v74, v71
	v_pk_mul_f32 v[58:59], v[64:65], v[64:65]
	v_pk_add_f32 v[76:77], v[76:77], v[78:79]
	v_pk_fma_f32 v[58:59], v[74:75], v[74:75], v[58:59]
	v_pk_add_f32 v[60:61], v[60:61], v[76:77]
	v_pk_add_f32 v[54:55], v[54:55], v[58:59]
	s_nop 0
	v_add_f32_e32 v23, v54, v55
	ds_bpermute_b32 v55, v245, v21
	ds_bpermute_b32 v58, v245, v23
	ds_bpermute_b32 v54, v245, v60
	s_waitcnt lgkmcnt(2)
	v_add_f32_e32 v21, v21, v55
	ds_bpermute_b32 v55, v245, v61
	s_waitcnt lgkmcnt(2)
	v_add_f32_e32 v23, v23, v58
	v_add_co_u32_e32 v58, vcc, s84, v66
	s_waitcnt lgkmcnt(0)
	v_pk_add_f32 v[54:55], v[60:61], v[54:55]
	v_addc_co_u32_e32 v59, vcc, 0, v67, vcc
	v_add_co_u32_e32 v62, vcc, s85, v66
	s_waitcnt vmcnt(1)
	v_mov_b64_e32 v[58:59], v[124:125]
	v_mov_b64_e32 v[60:61], v[126:127]
	s_nop 0
	v_addc_co_u32_e32 v63, vcc, 0, v67, vcc
	s_waitcnt vmcnt(0)
	v_mov_b64_e32 v[62:63], v[132:133]
	v_mov_b64_e32 v[64:65], v[134:135]
	v_and_b32_e32 v68, 0xffff0000, v58
	v_and_b32_e32 v72, 0xffff0000, v60
	v_lshlrev_b32_e32 v66, 16, v58
	v_lshlrev_b32_e32 v67, 16, v62
	v_and_b32_e32 v69, 0xffff0000, v62
	v_lshlrev_b32_e32 v70, 16, v59
	v_and_b32_e32 v62, 0xffff0000, v59
	v_lshlrev_b32_e32 v59, 16, v64
	v_lshlrev_b32_e32 v58, 16, v60
	v_and_b32_e32 v73, 0xffff0000, v64
	v_and_b32_e32 v64, 0xffff0000, v61
	v_mov_b32_e32 v76, v68
	v_mov_b32_e32 v77, v72
	v_lshlrev_b32_e32 v74, 16, v61
	v_mov_b32_e32 v60, v66
	v_mov_b32_e32 v61, v58
	v_pk_mul_f32 v[76:77], v[76:77], v[76:77]
	v_mov_b32_e32 v78, v62
	v_mov_b32_e32 v79, v64
	v_pk_fma_f32 v[60:61], v[60:61], v[60:61], v[76:77]
	v_mov_b32_e32 v76, v70
	v_mov_b32_e32 v77, v74
	v_pk_mul_f32 v[78:79], v[78:79], v[78:79]
	v_lshlrev_b32_e32 v71, 16, v63
	v_pk_fma_f32 v[76:77], v[76:77], v[76:77], v[78:79]
	v_and_b32_e32 v63, 0xffff0000, v63
	v_pk_add_f32 v[60:61], v[60:61], v[76:77]
	v_lshlrev_b32_e32 v75, 16, v65
	v_and_b32_e32 v65, 0xffff0000, v65
	v_add_f32_e32 v80, v60, v61
	v_pk_add_f32 v[60:61], v[66:67], v[68:69]
	v_pk_add_f32 v[76:77], v[70:71], v[62:63]
	v_pk_add_f32 v[78:79], v[74:75], v[64:65]
	v_pk_add_f32 v[60:61], v[60:61], v[76:77]
	v_pk_add_f32 v[76:77], v[58:59], v[72:73]
	v_mov_b32_e32 v72, v69
	v_mov_b32_e32 v64, v63
	v_mov_b32_e32 v58, v67
	v_pk_mul_f32 v[66:67], v[72:73], v[72:73]
	v_mov_b32_e32 v74, v71
	v_pk_mul_f32 v[62:63], v[64:65], v[64:65]
	v_pk_fma_f32 v[58:59], v[58:59], v[58:59], v[66:67]
	v_pk_fma_f32 v[62:63], v[74:75], v[74:75], v[62:63]
	v_pk_add_f32 v[76:77], v[76:77], v[78:79]
	v_pk_add_f32 v[58:59], v[58:59], v[62:63]
	v_pk_add_f32 v[60:61], v[60:61], v[76:77]
	v_add_f32_e32 v62, v58, v59
	ds_bpermute_b32 v59, v245, v80
	ds_bpermute_b32 v58, v245, v60
	ds_bpermute_b32 v72, v246, v52
	ds_bpermute_b32 v73, v246, v53
	ds_bpermute_b32 v74, v246, v56
	s_waitcnt lgkmcnt(4)
	v_add_f32_e32 v63, v80, v59
	ds_bpermute_b32 v59, v245, v61
	ds_bpermute_b32 v65, v246, v63
	ds_bpermute_b32 v75, v246, v57
	s_waitcnt lgkmcnt(4)
	v_pk_add_f32 v[52:53], v[52:53], v[72:73]
	ds_bpermute_b32 v72, v247, v52
	s_waitcnt lgkmcnt(3)
	v_pk_add_f32 v[58:59], v[60:61], v[58:59]
	ds_bpermute_b32 v60, v245, v62
	ds_bpermute_b32 v61, v246, v21
	s_waitcnt lgkmcnt(4)
	v_add_f32_e32 v65, v63, v65
	s_waitcnt lgkmcnt(3)
	v_pk_add_f32 v[56:57], v[56:57], v[74:75]
	ds_bpermute_b32 v73, v247, v53
	s_waitcnt lgkmcnt(2)
	v_add_f32_e32 v64, v62, v60
	ds_bpermute_b32 v60, v246, v11
	ds_bpermute_b32 v66, v246, v64
	s_waitcnt lgkmcnt(3)
	v_add_f32_e32 v21, v21, v61
	ds_bpermute_b32 v62, v246, v23
	ds_bpermute_b32 v74, v247, v56
	s_waitcnt lgkmcnt(3)
	v_add_f32_e32 v11, v11, v60
	ds_bpermute_b32 v60, v246, v13
	s_waitcnt lgkmcnt(3)
	v_add_f32_e32 v64, v64, v66
	ds_bpermute_b32 v66, v247, v11
	s_waitcnt lgkmcnt(3)
	v_add_f32_e32 v23, v23, v62
	ds_bpermute_b32 v75, v247, v57
	s_waitcnt lgkmcnt(2)
	v_add_f32_e32 v13, v13, v60
	ds_bpermute_b32 v60, v246, v15
	s_waitcnt lgkmcnt(2)
	v_add_f32_e32 v11, v11, v66
	ds_bpermute_b32 v66, v247, v13
	v_pk_add_f32 v[52:53], v[52:53], v[72:73]
	s_waitcnt lgkmcnt(2)
	v_pk_add_f32 v[56:57], v[56:57], v[74:75]
	s_waitcnt lgkmcnt(1)
	v_add_f32_e32 v15, v15, v60
	ds_bpermute_b32 v60, v246, v19
	s_waitcnt lgkmcnt(1)
	v_add_f32_e32 v13, v13, v66
	ds_bpermute_b32 v66, v247, v15
	ds_bpermute_b32 v72, v248, v52
	ds_bpermute_b32 v73, v248, v53
	s_waitcnt lgkmcnt(3)
	v_add_f32_e32 v19, v19, v60
	ds_bpermute_b32 v74, v248, v56
	s_waitcnt lgkmcnt(3)
	v_add_f32_e32 v15, v15, v66
	ds_bpermute_b32 v66, v247, v19
	ds_bpermute_b32 v75, v248, v57
	s_waitcnt lgkmcnt(3)
	v_pk_add_f32 v[52:53], v[52:53], v[72:73]
	ds_bpermute_b32 v72, v249, v52
	ds_bpermute_b32 v73, v249, v53
	s_waitcnt lgkmcnt(3)
	v_add_f32_e32 v19, v19, v66
	ds_bpermute_b32 v66, v247, v21
	s_waitcnt lgkmcnt(3)
	v_pk_add_f32 v[56:57], v[56:57], v[74:75]
	ds_bpermute_b32 v74, v249, v56
	ds_bpermute_b32 v75, v249, v57
	s_waitcnt lgkmcnt(3)
	v_pk_add_f32 v[52:53], v[52:53], v[72:73]
	s_waitcnt lgkmcnt(2)
	v_add_f32_e32 v21, v21, v66
	ds_bpermute_b32 v66, v247, v23
	ds_bpermute_b32 v72, v250, v52
	s_waitcnt lgkmcnt(2)
	v_pk_add_f32 v[56:57], v[56:57], v[74:75]
	ds_bpermute_b32 v73, v250, v53
	ds_bpermute_b32 v74, v250, v56
	s_waitcnt lgkmcnt(3)
	v_add_f32_e32 v23, v23, v66
	ds_bpermute_b32 v66, v247, v65
	ds_bpermute_b32 v75, v250, v57
	s_waitcnt lgkmcnt(3)
	v_pk_add_f32 v[52:53], v[52:53], v[72:73]
	ds_bpermute_b32 v60, v246, v54
	ds_bpermute_b32 v61, v246, v55
	s_waitcnt lgkmcnt(3)
	v_add_f32_e32 v65, v65, v66
	ds_bpermute_b32 v66, v247, v64
	s_waitcnt lgkmcnt(3)
	v_pk_add_f32 v[56:57], v[56:57], v[74:75]
	v_pk_mul_f32 v[74:75], v[52:53], s[26:27] op_sel_hi:[1,0]
	v_pk_mul_f32 v[72:73], v[56:57], s[26:27] op_sel_hi:[1,0]
	v_mov_b32_e32 v83, v74
	s_waitcnt lgkmcnt(0)
	v_add_f32_e32 v64, v64, v66
	ds_bpermute_b32 v66, v248, v11
	v_mov_b32_e32 v143, v74
	v_mov_b32_e32 v81, v75
	v_mov_b32_e32 v79, v72
	v_mov_b32_e32 v77, v73
	s_waitcnt lgkmcnt(0)
	v_add_f32_e32 v11, v11, v66
	ds_bpermute_b32 v66, v248, v13
	ds_bpermute_b32 v62, v246, v58
	ds_bpermute_b32 v63, v246, v59
	v_pk_add_f32 v[54:55], v[54:55], v[60:61]
	ds_bpermute_b32 v60, v247, v54
	s_waitcnt lgkmcnt(3)
	v_add_f32_e32 v13, v13, v66
	ds_bpermute_b32 v66, v248, v15
	s_waitcnt lgkmcnt(2)
	v_pk_add_f32 v[58:59], v[58:59], v[62:63]
	ds_bpermute_b32 v61, v247, v55
	ds_bpermute_b32 v62, v247, v58
	ds_bpermute_b32 v63, v247, v59
	s_waitcnt lgkmcnt(3)
	v_add_f32_e32 v15, v15, v66
	ds_bpermute_b32 v66, v248, v19
	s_waitcnt lgkmcnt(3)
	v_pk_add_f32 v[54:55], v[54:55], v[60:61]
	ds_bpermute_b32 v60, v248, v54
	s_waitcnt lgkmcnt(2)
	v_pk_add_f32 v[58:59], v[58:59], v[62:63]
	ds_bpermute_b32 v61, v248, v55
	s_waitcnt lgkmcnt(2)
	v_add_f32_e32 v19, v19, v66
	ds_bpermute_b32 v66, v248, v21
	ds_bpermute_b32 v62, v248, v58
	ds_bpermute_b32 v63, v248, v59
	s_waitcnt lgkmcnt(3)
	v_pk_add_f32 v[54:55], v[54:55], v[60:61]
	ds_bpermute_b32 v60, v249, v54
	s_waitcnt lgkmcnt(3)
	v_add_f32_e32 v21, v21, v66
	ds_bpermute_b32 v66, v248, v23
	s_waitcnt lgkmcnt(2)
	v_pk_add_f32 v[58:59], v[58:59], v[62:63]
	ds_bpermute_b32 v61, v249, v55
	ds_bpermute_b32 v62, v249, v58
	ds_bpermute_b32 v63, v249, v59
	s_waitcnt lgkmcnt(3)
	v_add_f32_e32 v23, v23, v66
	ds_bpermute_b32 v66, v248, v65
	s_waitcnt lgkmcnt(3)
	v_pk_add_f32 v[54:55], v[54:55], v[60:61]
	ds_bpermute_b32 v60, v250, v54
	s_waitcnt lgkmcnt(2)
	v_pk_add_f32 v[58:59], v[58:59], v[62:63]
	ds_bpermute_b32 v61, v250, v55
	s_waitcnt lgkmcnt(2)
	v_add_f32_e32 v65, v65, v66
	ds_bpermute_b32 v66, v248, v64
	ds_bpermute_b32 v62, v250, v58
	ds_bpermute_b32 v63, v250, v59
	s_waitcnt lgkmcnt(3)
	v_pk_add_f32 v[54:55], v[54:55], v[60:61]
	s_waitcnt lgkmcnt(2)
	v_add_f32_e32 v64, v64, v66
	ds_bpermute_b32 v66, v249, v11
	s_waitcnt lgkmcnt(1)
	v_pk_add_f32 v[58:59], v[58:59], v[62:63]
	v_pk_mul_f32 v[62:63], v[54:55], s[26:27] op_sel_hi:[1,0]
	v_pk_mul_f32 v[60:61], v[58:59], s[26:27] op_sel_hi:[1,0]
	v_mov_b32_e32 v71, v62
	s_waitcnt lgkmcnt(0)
	v_add_f32_e32 v11, v11, v66
	ds_bpermute_b32 v66, v249, v13
	v_mov_b32_e32 v69, v63
	v_mov_b32_e32 v67, v60
	s_waitcnt lgkmcnt(0)
	v_add_f32_e32 v13, v13, v66
	ds_bpermute_b32 v66, v249, v15
	s_waitcnt lgkmcnt(0)
	v_add_f32_e32 v15, v15, v66
	ds_bpermute_b32 v66, v249, v19
	s_waitcnt lgkmcnt(0)
	v_add_f32_e32 v19, v19, v66
	ds_bpermute_b32 v66, v249, v21
	s_waitcnt lgkmcnt(0)
	v_add_f32_e32 v21, v21, v66
	ds_bpermute_b32 v66, v249, v23
	s_waitcnt lgkmcnt(0)
	v_add_f32_e32 v23, v23, v66
	ds_bpermute_b32 v66, v249, v65
	s_waitcnt lgkmcnt(0)
	v_add_f32_e32 v65, v65, v66
	ds_bpermute_b32 v66, v249, v64
	s_waitcnt lgkmcnt(0)
	v_add_f32_e32 v64, v64, v66
	ds_bpermute_b32 v66, v250, v11
	s_waitcnt lgkmcnt(0)
	v_add_f32_e32 v82, v11, v66
	ds_bpermute_b32 v11, v250, v13
	v_pk_mul_f32 v[82:83], v[82:83], v[142:143]
	v_mov_b32_e32 v143, v75
	s_waitcnt lgkmcnt(0)
	v_add_f32_e32 v80, v13, v11
	ds_bpermute_b32 v11, v250, v15
	v_sub_f32_e32 v13, v82, v83
	v_pk_mul_f32 v[80:81], v[80:81], v[142:143]
	v_mov_b32_e32 v143, v72
	v_max_f32_e32 v74, 0, v13
	s_waitcnt lgkmcnt(0)
	v_add_f32_e32 v78, v15, v11
	ds_bpermute_b32 v11, v250, v19
	v_sub_f32_e32 v13, v80, v81
	v_pk_mul_f32 v[78:79], v[78:79], v[142:143]
	v_mov_b32_e32 v143, v73
	v_max_f32_e32 v75, 0, v13
	s_waitcnt lgkmcnt(0)
	v_add_f32_e32 v76, v19, v11
	v_sub_f32_e32 v13, v78, v79
	v_pk_mul_f32 v[76:77], v[76:77], v[142:143]
	v_max_f32_e32 v72, 0, v13
	v_sub_f32_e32 v13, v76, v77
	v_pk_add_f32 v[74:75], v[74:75], s[22:23] op_sel_hi:[1,0]
	v_max_f32_e32 v73, 0, v13
	v_mul_f32_e32 v13, 0x4b800000, v74
	v_cmp_gt_f32_e64 s[44:45], s86, v74
	v_cmp_gt_f32_e64 s[42:43], s86, v75
	v_pk_add_f32 v[72:73], v[72:73], s[22:23] op_sel_hi:[1,0]
	v_cndmask_b32_e64 v13, v74, v13, s[44:45]
	v_rsq_f32_e32 v74, v13
	v_mul_f32_e32 v13, 0x4b800000, v75
	v_cndmask_b32_e64 v13, v75, v13, s[42:43]
	v_cmp_gt_f32_e64 s[40:41], s86, v72
	v_rsq_f32_e32 v75, v13
	v_mul_f32_e32 v13, 0x4b800000, v72
	v_cndmask_b32_e64 v13, v72, v13, s[40:41]
	v_cmp_gt_f32_e32 vcc, s86, v73
	v_rsq_f32_e32 v72, v13
	v_mul_f32_e32 v13, 0x4b800000, v73
	v_cndmask_b32_e32 v13, v73, v13, vcc
	v_rsq_f32_e32 v73, v13
	v_pk_mul_f32 v[76:77], v[74:75], s[10:11] op_sel_hi:[1,0]
	ds_bpermute_b32 v11, v250, v21
	v_cndmask_b32_e64 v74, v74, v76, s[44:45]
	v_pk_mul_f32 v[78:79], v[72:73], s[10:11] op_sel_hi:[1,0]
	v_cndmask_b32_e64 v75, v75, v77, s[42:43]
	v_cndmask_b32_e32 v73, v73, v79, vcc
	s_branch .Llnv_us
	s_nop 0
	s_nop 0
	s_nop 0
	s_nop 0
	s_nop 0
	s_nop 0
	s_nop 0
	s_nop 0
	s_nop 0
	s_nop 0
	s_nop 0
	s_nop 0
	s_nop 0
	s_nop 0
	s_nop 0
.Llnv_usd:
	v_add_co_u32_e32 v76, vcc, s80, v50
	s_waitcnt lgkmcnt(0)
	v_add_f32_e32 v70, v21, v11
	v_addc_co_u32_e32 v77, vcc, 0, v51, vcc
	v_add_co_u32_e32 v76, vcc, s81, v50
	v_cndmask_b32_e64 v72, v72, v78, s[40:41]
	s_nop 0
	v_addc_co_u32_e32 v77, vcc, 0, v51, vcc
	v_add_co_u32_e32 v76, vcc, s91, v50
	ds_bpermute_b32 v11, v250, v23
	s_nop 0
	v_addc_co_u32_e32 v77, vcc, 0, v51, vcc
	v_add_co_u32_e32 v76, vcc, s11, v50
	s_waitcnt lgkmcnt(0)
	v_add_f32_e32 v68, v23, v11
	v_addc_co_u32_e32 v77, vcc, 0, v51, vcc
	v_add_co_u32_e32 v80, vcc, s80, v48
	ds_bpermute_b32 v11, v250, v65
	s_nop 0
	v_addc_co_u32_e32 v81, vcc, 0, v49, vcc
	v_mov_b32_e32 v143, v62
	v_pk_mul_f32 v[70:71], v[70:71], v[142:143]
	s_waitcnt lgkmcnt(0)
	v_add_f32_e32 v66, v65, v11
	ds_bpermute_b32 v11, v250, v64
	v_mov_b32_e32 v143, v63
	v_pk_mul_f32 v[68:69], v[68:69], v[142:143]
	v_mov_b32_e32 v143, v60
	v_pk_mul_f32 v[66:67], v[66:67], v[142:143]
	s_waitcnt lgkmcnt(0)
	v_add_f32_e32 v64, v64, v11
	v_mov_b32_e32 v65, v61
	v_mov_b32_e32 v143, v61
	v_pk_mul_f32 v[64:65], v[64:65], v[142:143]
	v_add_u32_e32 v11, 0x4200, v9
	s_waitcnt vmcnt(15)
	v_mov_b32_e32 v13, v150
	v_lshlrev_b32_e32 v78, 16, v13
	v_add_co_u32_e32 v80, vcc, s81, v48
	s_waitcnt vmcnt(14)
	v_mov_b32_e32 v15, v151
	v_lshlrev_b32_e32 v79, 16, v15
	v_addc_co_u32_e32 v81, vcc, 0, v49, vcc
	v_add_co_u32_e32 v80, vcc, s91, v48
	s_waitcnt vmcnt(13)
	v_mov_b32_e32 v19, v152
	v_lshlrev_b32_e32 v76, 16, v19
	v_addc_co_u32_e32 v81, vcc, 0, v49, vcc
	v_add_co_u32_e32 v80, vcc, s11, v48
	s_waitcnt vmcnt(12)
	v_mov_b32_e32 v21, v153
	v_lshlrev_b32_e32 v77, 16, v21
	v_addc_co_u32_e32 v81, vcc, 0, v49, vcc
	v_pk_fma_f32 v[78:79], v[56:57], s[26:27], v[78:79] op_sel_hi:[1,0,1] neg_lo:[1,0,0] neg_hi:[1,0,0]
	v_pk_fma_f32 v[76:77], v[52:53], s[26:27], v[76:77] op_sel_hi:[1,0,1] neg_lo:[1,0,0] neg_hi:[1,0,0]
	v_pk_mul_f32 v[78:79], v[78:79], v[72:73]
	v_pk_mul_f32 v[76:77], v[76:77], v[74:75]
	v_pk_fma_f32 v[78:79], v[42:43], v[78:79], v[40:41]
	v_pk_fma_f32 v[76:77], v[28:29], v[76:77], v[24:25]
	s_waitcnt vmcnt(11)
	v_mov_b32_e32 v13, v154
	v_lshlrev_b32_e32 v82, 16, v13
	v_sub_f32_e32 v13, v70, v71
	v_max_f32_e32 v62, 0, v13
	v_sub_f32_e32 v13, v68, v69
	v_max_f32_e32 v63, 0, v13
	v_sub_f32_e32 v13, v66, v67
	v_max_f32_e32 v60, 0, v13
	v_sub_f32_e32 v13, v64, v65
	v_pk_add_f32 v[62:63], v[62:63], s[22:23] op_sel_hi:[1,0]
	v_max_f32_e32 v61, 0, v13
	v_mul_f32_e32 v13, 0x4b800000, v62
	v_cmp_gt_f32_e64 s[44:45], s86, v62
	v_cmp_gt_f32_e64 s[42:43], s86, v63
	v_pk_add_f32 v[60:61], v[60:61], s[22:23] op_sel_hi:[1,0]
	v_cndmask_b32_e64 v13, v62, v13, s[44:45]
	v_rsq_f32_e32 v62, v13
	v_mul_f32_e32 v13, 0x4b800000, v63
	v_cndmask_b32_e64 v13, v63, v13, s[42:43]
	v_cmp_gt_f32_e64 s[40:41], s86, v60
	v_rsq_f32_e32 v63, v13
	v_mul_f32_e32 v13, 0x4b800000, v60
	v_cndmask_b32_e64 v13, v60, v13, s[40:41]
	v_cmp_gt_f32_e32 vcc, s86, v61
	v_rsq_f32_e32 v60, v13
	v_mul_f32_e32 v13, 0x4b800000, v61
	v_cndmask_b32_e32 v13, v61, v13, vcc
	v_rsq_f32_e32 v61, v13
	v_pk_mul_f32 v[64:65], v[62:63], s[10:11] op_sel_hi:[1,0]
	s_waitcnt vmcnt(10)
	v_mov_b32_e32 v15, v155
	v_lshlrev_b32_e32 v83, 16, v15
	v_cndmask_b32_e64 v62, v62, v64, s[44:45]
	v_pk_mul_f32 v[66:67], v[60:61], s[10:11] op_sel_hi:[1,0]
	v_cndmask_b32_e64 v63, v63, v65, s[42:43]
	v_cndmask_b32_e32 v61, v61, v67, vcc
	v_add_co_u32_e32 v64, vcc, s84, v50
	v_cndmask_b32_e64 v60, v60, v66, s[40:41]
	s_nop 0
	v_addc_co_u32_e32 v65, vcc, 0, v51, vcc
	v_add_co_u32_e32 v64, vcc, s85, v50
	s_waitcnt vmcnt(8)
	v_mov_b32_e32 v19, v156
	v_mov_b32_e32 v21, v157
	v_lshlrev_b32_e32 v81, 16, v21
	v_addc_co_u32_e32 v65, vcc, 0, v51, vcc
	v_add_co_u32_e32 v64, vcc, s82, v50
	v_lshlrev_b32_e32 v80, 16, v19
	s_nop 0
	v_addc_co_u32_e32 v65, vcc, 0, v51, vcc
	v_add_co_u32_e32 v50, vcc, s83, v50
	s_nop 0
	v_addc_co_u32_e32 v51, vcc, 0, v51, vcc
	v_add_co_u32_e32 v66, vcc, s84, v48
	v_pk_fma_f32 v[56:57], v[56:57], s[26:27], v[82:83] op_sel_hi:[1,0,1] neg_lo:[1,0,0] neg_hi:[1,0,0]
	s_nop 0
	v_addc_co_u32_e32 v67, vcc, 0, v49, vcc
	v_pk_fma_f32 v[52:53], v[52:53], s[26:27], v[80:81] op_sel_hi:[1,0,1] neg_lo:[1,0,0] neg_hi:[1,0,0]
	v_pk_mul_f32 v[56:57], v[56:57], v[72:73]
	v_pk_mul_f32 v[52:53], v[52:53], v[74:75]
	v_pk_fma_f32 v[56:57], v[46:47], v[56:57], v[44:45]
	v_pk_fma_f32 v[52:53], v[26:27], v[52:53], v[32:33]
	s_waitcnt vmcnt(7)
	v_mov_b32_e32 v13, v158
	v_lshlrev_b32_e32 v64, 16, v13
	v_add_co_u32_e32 v66, vcc, s85, v48
	s_waitcnt vmcnt(6)
	v_mov_b32_e32 v15, v159
	v_lshlrev_b32_e32 v65, 16, v15
	v_addc_co_u32_e32 v67, vcc, 0, v49, vcc
	v_add_co_u32_e32 v66, vcc, s82, v48
	v_pk_fma_f32 v[64:65], v[58:59], s[26:27], v[64:65] op_sel_hi:[1,0,1] neg_lo:[1,0,0] neg_hi:[1,0,0]
	s_nop 0
	v_addc_co_u32_e32 v67, vcc, 0, v49, vcc
	v_add_co_u32_e32 v48, vcc, s83, v48
	s_waitcnt vmcnt(4)
	v_mov_b32_e32 v19, v160
	v_mov_b32_e32 v21, v161
	v_lshlrev_b32_e32 v51, 16, v21
	v_addc_co_u32_e32 v49, vcc, 0, v49, vcc
	v_lshlrev_b32_e32 v50, 16, v19
	v_pk_fma_f32 v[50:51], v[54:55], s[26:27], v[50:51] op_sel_hi:[1,0,1] neg_lo:[1,0,0] neg_hi:[1,0,0]
	v_pk_mul_f32 v[64:65], v[64:65], v[60:61]
	v_pk_mul_f32 v[50:51], v[50:51], v[62:63]
	v_pk_fma_f32 v[64:65], v[42:43], v[64:65], v[40:41]
	v_pk_fma_f32 v[50:51], v[28:29], v[50:51], v[24:25]
	v_cvt_pk_bf16_f32 v65, v64, v65
	v_cvt_pk_bf16_f32 v64, v50, v51
	v_cvt_pk_bf16_f32 v51, v78, v79
	v_cvt_pk_bf16_f32 v50, v76, v77
	ds_write2_b64 v9, v[50:51], v[64:65] offset1:1
	v_add_u32_e32 v9, 16, v9
	s_waitcnt vmcnt(3)
	v_mov_b32_e32 v13, v162
	v_lshlrev_b32_e32 v50, 16, v13
	s_waitcnt vmcnt(2)
	v_mov_b32_e32 v15, v163
	v_lshlrev_b32_e32 v51, 16, v15
	v_pk_fma_f32 v[50:51], v[58:59], s[26:27], v[50:51] op_sel_hi:[1,0,1] neg_lo:[1,0,0] neg_hi:[1,0,0]
	s_waitcnt vmcnt(1)
	v_mov_b32_e32 v19, v164
	v_lshlrev_b32_e32 v48, 16, v19
	s_waitcnt vmcnt(0)
	v_mov_b32_e32 v21, v165
	v_lshlrev_b32_e32 v49, 16, v21
	v_pk_fma_f32 v[48:49], v[54:55], s[26:27], v[48:49] op_sel_hi:[1,0,1] neg_lo:[1,0,0] neg_hi:[1,0,0]
	v_pk_mul_f32 v[50:51], v[50:51], v[60:61]
	v_pk_mul_f32 v[48:49], v[48:49], v[62:63]
	v_pk_fma_f32 v[50:51], v[46:47], v[50:51], v[44:45]
	v_pk_fma_f32 v[48:49], v[26:27], v[48:49], v[32:33]
	v_cvt_pk_bf16_f32 v51, v50, v51
	v_cvt_pk_bf16_f32 v50, v48, v49
	v_cvt_pk_bf16_f32 v49, v56, v57
	v_cvt_pk_bf16_f32 v48, v52, v53
	ds_write2_b64 v11, v[48:49], v[50:51] offset1:1
	s_cbranch_scc0 .LBB0_177
	v_mul_u32_u24_e32 v128, 0x180, v7
	v_lshl_add_u64 v[24:25], v[128:129], 0, v[30:31]
	v_lshlrev_b64 v[24:25], 15, v[24:25]
	s_waitcnt lgkmcnt(0)
	s_barrier
	v_lshl_add_u64 v[28:29], v[0:1], 0, v[24:25]
	ds_read2_b64 v[24:27], v90 offset1:1
	v_mov_b32_e32 v7, v129
	v_lshl_add_u64 v[30:31], v[28:29], 0, v[6:7]
	v_mov_b32_e32 v9, v129
	v_mov_b32_e32 v11, v129
	s_waitcnt lgkmcnt(0)
	global_store_dwordx4 v[30:31], v[24:27], off
	ds_read2_b64 v[24:27], v91 offset1:1
	v_lshl_add_u64 v[30:31], v[28:29], 0, v[8:9]
	v_mov_b32_e32 v13, v129
	v_mov_b32_e32 v15, v129
	v_mov_b32_e32 v19, v129
	s_waitcnt lgkmcnt(0)
	global_store_dwordx4 v[30:31], v[24:27], off
	ds_read2_b64 v[24:27], v92 offset1:1
	v_lshl_add_u64 v[30:31], v[28:29], 0, v[10:11]
	v_mov_b32_e32 v21, v129
	v_add_u32_e32 v98, s23, v98
	s_movk_i32 s0, 0x5ff
	s_waitcnt lgkmcnt(0)
	global_store_dwordx4 v[30:31], v[24:27], off
	ds_read2_b64 v[24:27], v93 offset1:1
	v_lshl_add_u64 v[30:31], v[28:29], 0, v[12:13]
	v_mov_b32_e32 v23, v129
	v_cmp_lt_i32_e32 vcc, s0, v98
	v_subrev_u16_e32 v88, s23, v88
	s_waitcnt lgkmcnt(0)
	global_store_dwordx4 v[30:31], v[24:27], off
	ds_read2_b64 v[24:27], v94 offset1:1
	v_lshl_add_u64 v[30:31], v[28:29], 0, v[14:15]
	s_or_b64 s[12:13], vcc, s[12:13]
	s_waitcnt lgkmcnt(0)
	global_store_dwordx4 v[30:31], v[24:27], off
	ds_read2_b64 v[24:27], v95 offset1:1
	v_lshl_add_u64 v[30:31], v[28:29], 0, v[18:19]
	s_waitcnt lgkmcnt(0)
	global_store_dwordx4 v[30:31], v[24:27], off
	ds_read2_b64 v[24:27], v96 offset1:1
	v_lshl_add_u64 v[30:31], v[28:29], 0, v[20:21]
	v_lshl_add_u64 v[28:29], v[28:29], 0, v[22:23]
	s_waitcnt lgkmcnt(0)
	global_store_dwordx4 v[30:31], v[24:27], off
	ds_read2_b64 v[24:27], v97 offset1:1
	s_waitcnt lgkmcnt(0)
	global_store_dwordx4 v[28:29], v[24:27], off
	s_barrier
	s_andn2_b64 exec, exec, s[12:13]
	s_cbranch_execnz .LBB0_176
	s_or_b64 exec, exec, s[12:13]

.Lnm_pro:
	v_lshl_add_u64 v[112:113], s[88:89], 0, v[36:37]
	v_lshl_add_u64 v[114:115], s[88:89], 0, v[58:59]
	v_add_co_u32_e32 v112, vcc, 0x8a80000, v112
	s_nop 0
	v_addc_co_u32_e32 v113, vcc, 0, v113, vcc
	global_load_dwordx4 v[0:3], v[114:115], off
	global_load_dwordx4 v[4:7], v[114:115], off offset:1024
	global_load_dwordx4 v[8:11], v[112:113], off
	global_load_dwordx4 v[12:15], v[112:113], off offset:1024
	s_branch .LBB0_318
	s_nop 0
	s_nop 0
	s_nop 0
	s_nop 0
	s_nop 0
	s_nop 0
	s_nop 0
	s_nop 0
	s_nop 0
	s_nop 0
	s_nop 0
	s_nop 0
	s_nop 0
	s_nop 0
	s_nop 0
	s_nop 0
	s_nop 0
	s_nop 0
	s_nop 0
	s_nop 0
	s_nop 0
	s_nop 0
	s_nop 0
	s_nop 0
	s_nop 0
	s_nop 0
	s_nop 0
	s_nop 0
	s_nop 0
	s_nop 0
	s_nop 0
	s_nop 0
	s_nop 0
	s_nop 0
	s_nop 0
	s_nop 0
	s_nop 0
	s_nop 0
	s_nop 0
	s_nop 0
	s_nop 0
	s_nop 0
	s_nop 0
	s_nop 0
	s_nop 0
	s_nop 0
	s_nop 0
	s_nop 0
	s_nop 0
	s_nop 0
	s_nop 0
	s_nop 0
	s_nop 0
	s_nop 0
	s_nop 0
	s_nop 0
	s_nop 0
	s_nop 0
	s_nop 0
	s_nop 0
	s_nop 0
	s_nop 0
	s_nop 0
	s_nop 0
	s_nop 0
	s_nop 0
	s_nop 0
	s_nop 0
	s_nop 0
	s_nop 0
	s_nop 0
	s_nop 0
	s_nop 0
	s_nop 0
	s_nop 0
	s_nop 0
	s_nop 0
	s_nop 0
	s_nop 0
	s_nop 0
	s_nop 0
	s_nop 0
	s_nop 0
	s_nop 0
	s_nop 0
	s_nop 0
	s_nop 0
	s_nop 0
	s_nop 0
	s_nop 0
	s_nop 0
	s_nop 0
	s_nop 0
	s_nop 0
	s_nop 0
	s_nop 0
	s_nop 0
	s_nop 0
	s_nop 0
	s_nop 0
	s_nop 0
	s_nop 0
	s_nop 0
	s_nop 0
	s_nop 0
	s_nop 0
	s_nop 0
	s_nop 0
	s_nop 0
	s_nop 0
	s_nop 0
	s_nop 0
	s_nop 0
	s_nop 0
	s_nop 0
	s_nop 0
	s_nop 0
	s_nop 0
	s_nop 0
	s_nop 0
	s_nop 0
	s_nop 0
	s_nop 0
	s_nop 0
	s_nop 0
	s_nop 0
	s_nop 0
	s_nop 0
	s_nop 0
	s_nop 0
	s_nop 0
	s_nop 0
	s_nop 0
	s_nop 0
	s_nop 0
	s_nop 0
	s_nop 0
	s_nop 0
	s_nop 0
	s_nop 0
	s_nop 0
	s_nop 0
	s_nop 0
	s_nop 0
	s_nop 0
	s_nop 0
	s_nop 0
	s_nop 0
	s_nop 0
	s_nop 0
	s_nop 0
	s_nop 0
	s_nop 0
	s_nop 0
	s_nop 0
	s_nop 0
	s_nop 0
	s_nop 0
	s_nop 0
	s_nop 0
	s_nop 0
	s_nop 0
	s_nop 0
	s_nop 0
	s_nop 0
	s_nop 0
	s_nop 0
	s_nop 0
	s_nop 0
	s_nop 0
	s_nop 0
	s_nop 0
	s_nop 0
	s_nop 0
	s_nop 0
	s_nop 0
	s_nop 0
	s_nop 0
	s_nop 0
	s_nop 0
	s_nop 0
	s_nop 0
	s_nop 0
	s_nop 0
	s_nop 0
	s_nop 0
	s_nop 0
	s_nop 0
	s_nop 0
	s_nop 0
	s_nop 0
	s_nop 0
	s_nop 0
	s_nop 0
	s_nop 0
	s_nop 0
	s_nop 0
	s_nop 0
	s_nop 0
	s_nop 0
	s_nop 0
	s_nop 0
	s_nop 0
	s_nop 0
	s_nop 0
	s_nop 0
	s_nop 0
	s_nop 0
	s_nop 0
	s_nop 0
	s_nop 0
	s_nop 0
	s_nop 0
	s_nop 0
	s_nop 0
	s_nop 0
	s_nop 0
	s_nop 0
	s_nop 0
	s_nop 0
	s_nop 0
	s_nop 0
	s_nop 0
	s_nop 0
	s_nop 0
	s_nop 0
	s_nop 0
	s_nop 0
	s_nop 0
	s_nop 0
	s_nop 0
	s_nop 0
	s_nop 0
	s_nop 0
	s_nop 0
	s_nop 0
	s_nop 0
	s_nop 0
	s_nop 0
	s_nop 0
	s_nop 0
	s_nop 0
	s_nop 0
	s_nop 0
	s_nop 0
	s_nop 0
	s_nop 0
	s_nop 0
	s_nop 0
	s_nop 0
	s_nop 0
	s_nop 0
	s_nop 0
	s_nop 0
	s_nop 0
	s_nop 0
	s_nop 0
	s_nop 0
	s_nop 0
	s_nop 0
	s_nop 0
	s_nop 0
	s_nop 0
	s_nop 0
	s_nop 0
	s_nop 0
	s_nop 0
	s_nop 0
	s_nop 0
	s_nop 0
	s_nop 0
	s_nop 0
	s_nop 0
	s_nop 0
	s_nop 0
	s_nop 0
	s_nop 0
	s_nop 0
	s_nop 0
	s_nop 0
	s_nop 0
	s_nop 0
	s_nop 0
	s_nop 0
	s_nop 0
	s_nop 0
	s_nop 0
	s_nop 0
	s_nop 0
	s_nop 0
	s_nop 0
	s_nop 0
	s_nop 0
.Lfbp_addr:
	v_alignbit_b32 v212, v191, v190, 2
	v_add_u32_e32 v214, v201, v212
	v_ashrrev_i32_e32 v215, 31, v214
	v_lshlrev_b64 v[236:237], 11, v[214:215]
	v_lshl_add_u64 v[236:237], s[6:7], 0, v[236:237]
	v_lshl_add_u64 v[236:237], v[236:237], 0, v[128:129]
	v_add_u32_e32 v214, v202, v212
	v_ashrrev_i32_e32 v215, 31, v214
	v_lshlrev_b64 v[238:239], 11, v[214:215]
	v_lshl_add_u64 v[238:239], s[6:7], 0, v[238:239]
	v_lshl_add_u64 v[238:239], v[238:239], 0, v[128:129]
	v_mbcnt_lo_u32_b32 v220, -1, 0
	v_mbcnt_hi_u32_b32 v220, -1, v220
	v_and_b32_e32 v220, 32, v220
	v_lshrrev_b32_e32 v220, 2, v220
	v_mov_b32_e32 v221, 0
	v_lshl_add_u64 v[236:237], v[236:237], 0, v[220:221]
	v_lshl_add_u64 v[238:239], v[238:239], 0, v[220:221]
	s_branch .Lfbp_addrd

.Llnv_us:
	v_add_co_u32_e32 v166, vcc, s80, v50
	s_nop 0
	v_addc_co_u32_e32 v167, vcc, 0, v51, vcc
	global_load_ushort v150, v[166:167], off offset:1024
	v_add_co_u32_e32 v166, vcc, s81, v50
	s_nop 0
	v_addc_co_u32_e32 v167, vcc, 0, v51, vcc
	global_load_ushort v151, v[166:167], off offset:1024
	v_add_co_u32_e32 v166, vcc, s91, v50
	s_nop 0
	v_addc_co_u32_e32 v167, vcc, 0, v51, vcc
	global_load_ushort v152, v[166:167], off offset:1024
	v_add_co_u32_e32 v166, vcc, s11, v50
	s_nop 0
	v_addc_co_u32_e32 v167, vcc, 0, v51, vcc
	global_load_ushort v153, v[166:167], off offset:1024
	v_add_co_u32_e32 v166, vcc, s80, v48
	s_nop 0
	v_addc_co_u32_e32 v167, vcc, 0, v49, vcc
	global_load_ushort v154, v[166:167], off offset:1024
	v_add_co_u32_e32 v166, vcc, s81, v48
	s_nop 0
	v_addc_co_u32_e32 v167, vcc, 0, v49, vcc
	global_load_ushort v155, v[166:167], off offset:1024
	v_add_co_u32_e32 v166, vcc, s91, v48
	s_nop 0
	v_addc_co_u32_e32 v167, vcc, 0, v49, vcc
	global_load_ushort v156, v[166:167], off offset:1024
	v_add_co_u32_e32 v166, vcc, s11, v48
	s_nop 0
	v_addc_co_u32_e32 v167, vcc, 0, v49, vcc
	global_load_ushort v157, v[166:167], off offset:1024
	v_add_co_u32_e32 v166, vcc, s84, v50
	s_nop 0
	v_addc_co_u32_e32 v167, vcc, 0, v51, vcc
	global_load_ushort v158, v[166:167], off offset:1024
	v_add_co_u32_e32 v166, vcc, s85, v50
	s_nop 0
	v_addc_co_u32_e32 v167, vcc, 0, v51, vcc
	global_load_ushort v159, v[166:167], off offset:1024
	v_add_co_u32_e32 v166, vcc, s82, v50
	s_nop 0
	v_addc_co_u32_e32 v167, vcc, 0, v51, vcc
	global_load_ushort v160, v[166:167], off offset:1024
	v_add_co_u32_e32 v166, vcc, s83, v50
	s_nop 0
	v_addc_co_u32_e32 v167, vcc, 0, v51, vcc
	global_load_ushort v161, v[166:167], off offset:1024
	v_add_co_u32_e32 v166, vcc, s84, v48
	s_nop 0
	v_addc_co_u32_e32 v167, vcc, 0, v49, vcc
	global_load_ushort v162, v[166:167], off offset:1024
	v_add_co_u32_e32 v166, vcc, s85, v48
	s_nop 0
	v_addc_co_u32_e32 v167, vcc, 0, v49, vcc
	global_load_ushort v163, v[166:167], off offset:1024
	v_add_co_u32_e32 v166, vcc, s82, v48
	s_nop 0
	v_addc_co_u32_e32 v167, vcc, 0, v49, vcc
	global_load_ushort v164, v[166:167], off offset:1024
	v_add_co_u32_e32 v166, vcc, s83, v48
	s_nop 0
	v_addc_co_u32_e32 v167, vcc, 0, v49, vcc
	global_load_ushort v165, v[166:167], off offset:1024
	s_branch .Llnv_usd
